# team barrier: single arrival counter polled to 4*(round+1), L1 invalidate issued before the poll; gridDim==256 guard
# baseline (speedup 1.0000x reference)
.LBB0_5:
	s_or_b64 exec, exec, s[0:1]
	s_add_u32 s24, s96, 0xea80000
	s_addc_u32 s25, s97, 0
	s_add_u32 s28, s96, 0x6080000
	s_addc_u32 s29, s97, 0
	s_add_u32 s20, s96, 0x8080000
	s_addc_u32 s35, s97, 0
	s_add_u32 s6, s96, 0x4200000
	s_addc_u32 s7, s97, 0
	v_writelane_b32 v250, s6, 50
	s_cmpk_lt_i32 s69, 0x200
	v_lshrrev_b32_e32 v1, 20, v0
	v_writelane_b32 v250, s7, 51
	s_cselect_b64 s[6:7], -1, 0
	v_writelane_b32 v250, s6, 52
	s_cmpk_eq_i32 s98, 0x100
	v_lshrrev_b32_e32 v0, 10, v0
	v_writelane_b32 v250, s7, 53
	s_cselect_b64 s[6:7], -1, 0
	v_writelane_b32 v250, s6, 54
	s_and_b32 s1, s69, 7
	s_lshr_b32 s86, s69, 3
	v_writelane_b32 v250, s7, 55
	s_ashr_i32 s6, s69, 3
	s_and_b32 s6, s6, -8
	s_or_b32 s87, s6, s1
	s_cmp_lg_u32 0, -1
	s_cselect_b64 s[30:31], -1, 0
	s_lshl_b32 s16, s69, 3
	s_lshl_b32 s83, s98, 3
	s_add_u32 s6, s96, 0x4e00000
	s_addc_u32 s7, s97, 0
	v_writelane_b32 v250, s6, 56
	s_ashr_i32 s1, s69, 31
	s_and_b32 s9, s29, 0xffff
	v_writelane_b32 v250, s7, 57
	v_writelane_b32 v250, s1, 58
	s_lshr_b32 s1, s1, 29
	s_add_i32 s1, s69, s1
	s_ashr_i32 s6, s1, 3
	s_and_b32 s1, s1, -8
	v_writelane_b32 v250, s6, 59
	s_sub_i32 s6, s69, s1
	s_ashr_i32 s1, s98, 31
	s_add_u32 s10, s96, 0xe280000
	v_writelane_b32 v250, s1, 60
	s_addc_u32 s11, s97, 0
	v_writelane_b32 v250, s10, 61
	s_mul_i32 s0, s99, s98
	v_or_b32_e32 v0, v0, v1
	v_writelane_b32 v250, s11, 62
	s_add_u32 s10, s96, 0xeb15100
	s_addc_u32 s11, s97, 0
	v_writelane_b32 v250, s10, 63
	s_mul_i32 s90, s0, s8
	v_readlane_b32 s36, v250, 2
	v_writelane_b32 v249, s11, 0
	s_add_u32 s10, s96, 0xeb11000
	s_addc_u32 s11, s97, 0
	s_not_b32 s1, s69
	v_writelane_b32 v249, s10, 1
	s_add_i32 s1, s98, s1
	s_cmp_lt_i32 s1, 64
	v_writelane_b32 v249, s11, 2
	v_writelane_b32 v249, s1, 3
	s_cselect_b64 s[10:11], -1, 0
	v_writelane_b32 v249, s10, 4
	s_movk_i32 s1, 0x3ff
	v_and_or_b32 v1, v0, s1, v220
	v_writelane_b32 v249, s11, 5
	s_add_u32 s10, s96, 0x4600000
	s_addc_u32 s11, s97, 0
	v_writelane_b32 v249, s10, 6
	v_readlane_b32 s46, v250, 12
	v_readlane_b32 s47, v250, 13
	v_writelane_b32 v249, s11, 7
	s_add_u32 s10, s96, 0xeb10000
	s_addc_u32 s11, s97, 0
	s_add_u32 s68, s96, 0xe680000
	s_addc_u32 s80, s97, 0
	s_lshl_b32 s91, s69, 9
	s_lshl_b32 s81, s98, 9
	v_writelane_b32 v249, s10, 8
	s_cmp_eq_u32 s69, 0
	s_cselect_b64 s[0:1], -1, 0
	v_writelane_b32 v249, s11, 9
	v_writelane_b32 v249, s0, 10
	s_cmpk_lt_i32 s69, 0x20a0
	s_mov_b32 s8, s28
	v_writelane_b32 v249, s1, 11
	s_cselect_b64 s[0:1], -1, 0
	v_writelane_b32 v249, s0, 12
	s_brev_b32 s10, 64
	v_cmp_eq_u32_e64 s[22:23], 0, v1
	v_writelane_b32 v249, s1, 13
	s_add_u32 s0, s96, 0xe080000
	s_addc_u32 s1, s97, 0
	s_add_u32 s70, s96, 0x5880000
	v_writelane_b32 v249, s0, 14
	s_addc_u32 s71, s97, 0
	s_mov_b32 s34, s20
	v_writelane_b32 v249, s1, 15
	s_add_u32 s0, s46, 0x1000
	s_addc_u32 s1, s47, 0
	v_writelane_b32 v249, s0, 16
	v_readlane_b32 s37, v250, 3
	s_mov_b32 s12, 0x41980000
	v_writelane_b32 v249, s1, 17
	s_add_u32 s0, s96, 0x5680000
	s_addc_u32 s1, s97, 0
	v_writelane_b32 v249, s0, 18
	s_mov_b32 s14, 0x41c80000
	v_mbcnt_lo_u32_b32 v227, -1, 0
	v_writelane_b32 v249, s1, 19
	s_add_u32 s0, s96, 0x5200000
	s_addc_u32 s1, s97, 0
	v_writelane_b32 v249, s0, 20
	v_mov_b32_e32 v0, 0
	s_mov_b32 s13, 0x41c00000
	v_writelane_b32 v249, s1, 21
	s_add_u32 s0, s96, 0x5e80000
	s_addc_u32 s1, s97, 0
	v_writelane_b32 v249, s0, 22
	s_mov_b32 s15, 0x41d00000
	v_mov_b32_e32 v221, 0x358637bd
	v_writelane_b32 v249, s1, 23
	s_add_u32 s0, s96, 0x3700000
	s_addc_u32 s1, s97, 0
	v_writelane_b32 v249, s0, 24
	v_mov_b32_e32 v222, 1
	v_mov_b32_e32 v223, 0x42800000
	v_writelane_b32 v249, s1, 25
	s_add_u32 s0, s96, 0x2100000
	s_addc_u32 s1, s97, 0
	v_writelane_b32 v249, s0, 26
	v_mov_b32_e32 v224, 0xfff
	v_mov_b32_e32 v225, 0x1800
	v_writelane_b32 v249, s1, 27
	s_add_u32 s0, s96, 0x1600000
	s_addc_u32 s1, s97, 0
	v_writelane_b32 v249, s0, 28
	s_cmp_eq_u64 s[96:97], 0
	v_mov_b32_e32 v226, 0xff800000
	v_writelane_b32 v249, s1, 29
	s_cselect_b64 s[0:1], -1, 0
	v_writelane_b32 v249, s0, 30
	v_mbcnt_hi_u32_b32 v228, -1, v227
	v_not_b32_e32 v229, 63
	v_writelane_b32 v249, s1, 31
	s_add_u32 s0, s96, 0xeb11300
	s_addc_u32 s1, s97, 0
	v_writelane_b32 v249, s0, 32
	v_mov_b32_e32 v230, 0xffffd0c0
	v_mov_b32_e32 v231, 0xffffd3c0
	v_writelane_b32 v249, s1, 33
	s_add_u32 s0, s96, 0xeb11500
	s_addc_u32 s1, s97, 0
	v_writelane_b32 v249, s0, 34
	v_mov_b32_e32 v232, 0xffffd4c0
	s_movk_i32 s89, 0x1800
	v_writelane_b32 v249, s1, 35
	s_add_u32 s0, s96, 0xeb11600
	s_addc_u32 s1, s97, 0
	v_writelane_b32 v249, s0, 36
	s_movk_i32 s19, 0x1200
	s_mov_b32 s17, 0
	v_writelane_b32 v249, s1, 37
	s_add_u32 s0, s96, 0xeb11700
	s_addc_u32 s1, s97, 0
	v_writelane_b32 v249, s0, 38
	s_mov_b32 s18, 0x3e38aa3b
	s_mov_b64 s[36:37], 0x80
	v_writelane_b32 v249, s1, 39
	s_add_u32 s0, s96, 0xeb11800
	s_addc_u32 s1, s97, 0
	v_writelane_b32 v249, s0, 40
	s_mov_b64 s[26:27], 0x400c0
	v_readlane_b32 s38, v250, 4
	v_writelane_b32 v249, s1, 41
	s_add_u32 s0, s96, 0xeb11900
	s_addc_u32 s1, s97, 0
	v_writelane_b32 v249, s0, 42
	v_readlane_b32 s39, v250, 5
	v_readlane_b32 s40, v250, 6
	v_writelane_b32 v249, s1, 43
	s_add_u32 s0, s96, 0xeb11a00
	s_addc_u32 s1, s97, 0
	v_writelane_b32 v249, s0, 44
	v_readlane_b32 s41, v250, 7
	v_readlane_b32 s42, v250, 8
	v_writelane_b32 v249, s1, 45
	s_add_u32 s0, s96, 0xeb11b00
	s_addc_u32 s1, s97, 0
	v_writelane_b32 v249, s0, 46
	v_readlane_b32 s43, v250, 9
	v_readlane_b32 s44, v250, 10
	v_writelane_b32 v249, s1, 47
	s_add_u32 s0, s96, 0xeb11c00
	s_addc_u32 s1, s97, 0
	v_writelane_b32 v249, s0, 48
	v_readlane_b32 s45, v250, 11
	v_readlane_b32 s48, v250, 14
	v_writelane_b32 v249, s1, 49
	s_add_u32 s0, s96, 0xeb11d00
	s_addc_u32 s1, s97, 0
	v_writelane_b32 v249, s0, 50
	v_readlane_b32 s49, v250, 15
	v_readlane_b32 s50, v250, 16
	v_writelane_b32 v249, s1, 51
	s_add_u32 s0, s96, 0xeb11e00
	s_addc_u32 s1, s97, 0
	v_writelane_b32 v249, s0, 52
	v_readlane_b32 s51, v250, 17
	s_nop 0
	v_writelane_b32 v249, s1, 53
	s_add_u32 s0, s96, 0xeb11f00
	s_addc_u32 s1, s97, 0
	v_writelane_b32 v249, s0, 54
	s_nop 1
	v_writelane_b32 v249, s1, 55
	s_add_u32 s0, s96, 0xeb12000
	s_addc_u32 s1, s97, 0
	v_writelane_b32 v249, s0, 56
	s_nop 1
	v_writelane_b32 v249, s1, 57
	s_add_u32 s0, s96, 0xeb12100
	s_addc_u32 s1, s97, 0
	v_writelane_b32 v249, s0, 58
	s_nop 1
	v_writelane_b32 v249, s1, 59
	s_add_u32 s0, s96, 0xeb12200
	s_addc_u32 s1, s97, 0
	v_writelane_b32 v249, s0, 60
	s_nop 1
	v_writelane_b32 v249, s1, 61
	s_add_u32 s0, s96, 0xeb12300
	s_addc_u32 s1, s97, 0
	v_writelane_b32 v249, s0, 62
	s_nop 1
	v_writelane_b32 v249, s1, 63
	s_add_u32 s0, s96, 0xeb12400
	s_addc_u32 s1, s97, 0
	v_writelane_b32 v248, s0, 0
	s_cmp_eq_u32 s3, 15
	s_nop 0
	v_writelane_b32 v248, s1, 1
	s_cselect_b64 s[0:1], -1, 0
	v_writelane_b32 v248, s0, 2
	s_cmp_eq_u32 s3, 14
	s_nop 0
	v_writelane_b32 v248, s1, 3
	s_cselect_b64 s[0:1], -1, 0
	v_writelane_b32 v248, s0, 4
	s_cmp_eq_u32 s3, 13
	s_nop 0
	v_writelane_b32 v248, s1, 5
	s_cselect_b64 s[0:1], -1, 0
	v_writelane_b32 v248, s0, 6
	s_cmp_eq_u32 s3, 12
	s_nop 0
	v_writelane_b32 v248, s1, 7
	s_cselect_b64 s[0:1], -1, 0
	v_writelane_b32 v248, s0, 8
	s_cmp_eq_u32 s3, 11
	s_nop 0
	v_writelane_b32 v248, s1, 9
	s_cselect_b64 s[0:1], -1, 0
	v_writelane_b32 v248, s0, 10
	s_cmp_eq_u32 s3, 10
	s_nop 0
	v_writelane_b32 v248, s1, 11
	s_cselect_b64 s[0:1], -1, 0
	v_writelane_b32 v248, s0, 12
	s_cmp_eq_u32 s3, 9
	s_nop 0
	v_writelane_b32 v248, s1, 13
	s_cselect_b64 s[0:1], -1, 0
	v_writelane_b32 v248, s0, 14
	s_cmp_eq_u32 s3, 8
	s_nop 0
	v_writelane_b32 v248, s1, 15
	s_cselect_b64 s[0:1], -1, 0
	v_writelane_b32 v248, s0, 16
	s_cmp_eq_u32 s3, 7
	s_nop 0
	v_writelane_b32 v248, s1, 17
	s_cselect_b64 s[0:1], -1, 0
	v_writelane_b32 v248, s0, 18
	s_cmp_eq_u32 s3, 6
	s_nop 0
	v_writelane_b32 v248, s1, 19
	s_cselect_b64 s[0:1], -1, 0
	v_writelane_b32 v248, s0, 20
	s_cmp_eq_u32 s3, 5
	s_nop 0
	v_writelane_b32 v248, s1, 21
	s_cselect_b64 s[0:1], -1, 0
	v_writelane_b32 v248, s0, 22
	s_cmp_eq_u32 s3, 4
	s_nop 0
	v_writelane_b32 v248, s1, 23
	s_cselect_b64 s[0:1], -1, 0
	v_writelane_b32 v248, s0, 24
	s_cmp_eq_u32 s3, 3
	s_nop 0
	v_writelane_b32 v248, s1, 25
	s_cselect_b64 s[0:1], -1, 0
	v_writelane_b32 v248, s0, 26
	s_cmp_eq_u32 s3, 2
	s_nop 0
	v_writelane_b32 v248, s1, 27
	s_cselect_b64 s[0:1], -1, 0
	v_writelane_b32 v248, s0, 28
	s_cmp_eq_u32 s3, 1
	s_nop 0
	v_writelane_b32 v248, s1, 29
	s_cselect_b64 s[0:1], -1, 0
	v_writelane_b32 v248, s0, 30
	s_cmp_eq_u32 s3, 0
	s_nop 0
	v_writelane_b32 v248, s1, 31
	s_cselect_b64 s[0:1], -1, 0
	v_writelane_b32 v248, s0, 32
	s_nop 1
	v_writelane_b32 v248, s1, 33
	s_lshl_b32 s0, s2, 2
	s_add_u32 s0, s4, s0
	s_addc_u32 s1, s5, 0
	s_add_u32 s2, s0, 0x1400
	s_addc_u32 s3, s1, 0
	v_writelane_b32 v248, s2, 34
	s_add_u32 s0, s0, 0x2400
	s_addc_u32 s1, s1, 0
	v_writelane_b32 v248, s3, 35
	v_writelane_b32 v248, s0, 36
	s_mov_b32 s3, 0x20000
	s_mov_b32 s11, s3
	v_writelane_b32 v248, s1, 37
	v_writelane_b32 v248, s8, 38
	s_add_u32 s0, s96, 0xeb14500
	s_addc_u32 s1, s97, 0
	v_writelane_b32 v248, s9, 39
	v_writelane_b32 v248, s10, 40
	v_writelane_b32 v248, s11, 41
	v_writelane_b32 v248, s0, 42
	s_brev_b32 s2, 32
	s_mov_b32 s4, 0x40400000
	v_writelane_b32 v248, s1, 43
	s_add_u32 s0, s96, 0xeb14600
	s_addc_u32 s1, s97, 0
	v_writelane_b32 v248, s0, 44
	s_mov_b32 s8, 0x41300000
	s_mov_b32 s10, 0x41880000
	v_writelane_b32 v248, s1, 45
	v_writelane_b32 v248, s6, 46
	s_lshr_b32 s0, s6, 31
	v_writelane_b32 v248, s0, 47
	s_lshl_b32 s0, s69, 6
	v_writelane_b32 v248, s0, 48
	s_lshl_b32 s0, s98, 6
	v_writelane_b32 v248, s0, 49
	s_add_u32 s0, s96, 0xe68c000
	v_writelane_b32 v248, s0, 50
	s_addc_u32 s0, s97, 0
	v_writelane_b32 v248, s0, 51
	s_add_u32 s0, s96, 0x8080020
	s_addc_u32 s1, s97, 0
	v_writelane_b32 v248, s0, 52
	s_lshl_b32 s82, s98, 1
	s_mov_b32 s6, 0x41100000
	v_writelane_b32 v248, s1, 53
	v_writelane_b32 v248, s0, 54
	s_mov_b32 s5, 0x41000000
	s_mov_b32 s7, 0x41200000
	v_writelane_b32 v248, s1, 55
	v_writelane_b32 v248, s2, 56
	v_writelane_b32 v248, s3, 57
	v_writelane_b32 v248, s16, 58
	s_add_i32 s0, s16, 0xfffeff00
	v_writelane_b32 v248, s0, 59
	s_lshl_b32 s0, s69, 1
	v_writelane_b32 v248, s0, 60
	s_add_i32 s0, 0, 0x240f0
	v_writelane_b32 v248, s0, 61
	s_add_i32 s0, 0, 0x240f4
	v_writelane_b32 v248, s0, 62
	v_writelane_b32 v248, s22, 63
	s_mov_b32 s9, 0x41800000
	s_mov_b32 s11, 0x41900000
	v_writelane_b32 v243, s23, 0
	v_writelane_b32 v243, s84, 1
	s_mov_b32 s3, 0xff800000
	s_add_i32 s33, 0, 0x12000
	v_writelane_b32 v243, s85, 2
	v_writelane_b32 v243, s28, 3
	s_mov_b32 s0, 0
	s_nop 0
	v_writelane_b32 v243, s29, 4
	v_writelane_b32 v243, s34, 5
	s_nop 1
	v_writelane_b32 v243, s35, 6
	v_writelane_b32 v243, s86, 7
	v_writelane_b32 v243, s87, 8
	v_writelane_b32 v243, s83, 9
	v_writelane_b32 v243, s68, 10
	v_writelane_b32 v243, s80, 11
	v_writelane_b32 v243, s90, 12
	v_writelane_b32 v243, s91, 13
	v_writelane_b32 v243, s81, 14
	v_writelane_b32 v243, s82, 15
	v_writelane_b32 v243, s69, 16
	v_writelane_b32 v243, s70, 17
	s_nop 1
	v_writelane_b32 v243, s71, 18
	v_writelane_b32 v243, 0, 60
	s_branch .LBB0_9

.LBB0_404:
	v_readlane_b32 s0, v243, 19
	v_readlane_b32 s22, v243, 20
	s_cmp_lg_u32 s0, 20
	s_mul_hi_u32 s16, s22, 0xcccccccd
	s_cselect_b64 s[0:1], -1, 0
	s_lshr_b32 s16, s16, 3
	s_mul_i32 s16, s16, 10
	s_sub_i32 s16, s22, s16
	s_cmp_lg_u32 s16, 6
	s_cselect_b64 s[22:23], -1, 0
	s_and_b64 s[0:1], s[0:1], s[22:23]
	s_andn2_b64 vcc, exec, s[0:1]
	s_cbranch_vccnz .LBB0_8
	s_waitcnt vmcnt(0)
	s_waitcnt vmcnt(0) lgkmcnt(0)
	s_barrier
	s_and_saveexec_b64 s[22:23], s[84:85]
	s_cbranch_execz .LBB0_7
	s_cmpk_lg_u32 s98, 0x100
	s_cbranch_scc1 .Ltb_full
	v_readlane_b32 s0, v243, 19
	s_mov_b32 s1, 0xc9f24
	s_lshr_b32 s1, s1, s0
	s_and_b32 s1, s1, 1
	s_cmp_eq_u32 s1, 0
	s_cbranch_scc1 .Ltb_full
	v_readlane_b32 s0, v243, 16
	s_and_b32 s0, s0, 63
	s_lshl_b32 s0, s0, 5
	s_add_u32 s28, s96, 0xeb12d00
	s_addc_u32 s29, s97, 0
	s_add_u32 s28, s28, s0
	s_addc_u32 s29, s29, 0
	v_mov_b32_e32 v1, 1
	global_atomic_add v0, v1, s[28:29]
	buffer_inv sc1
	v_readlane_b32 s0, v243, 60
	s_add_i32 s0, s0, 1
	v_writelane_b32 v243, s0, 60
	s_lshl_b32 s0, s0, 2
.Ltb_wait:
	global_load_dword v2, v0, s[28:29] sc1
	s_waitcnt vmcnt(0)
	v_readfirstlane_b32 s1, v2
	s_cmp_ge_u32 s1, s0
	s_cbranch_scc1 .Ltb_go
	s_sleep 1
	s_branch .Ltb_wait
.Ltb_go:
	s_branch .LBB0_7
.Ltb_full:
	v_readlane_b32 s0, v248, 61
	s_waitcnt vmcnt(0) expcnt(0) lgkmcnt(0)
	s_nop 0
	v_mov_b32_e32 v1, s0
	ds_read_b32 v3, v1
	v_readlane_b32 s0, v248, 62
	s_waitcnt lgkmcnt(0)
	v_cmp_ne_u32_e32 vcc, 0, v3
	v_mov_b32_e32 v1, s0
	ds_read_b32 v2, v1
	s_cbranch_vccnz .LBB0_421
	s_mov_b32 s0, 1
	s_branch .LBB0_409
